# branch-test chain shortened at both attention block heads: the row-max copy for v_permlane32_swap issued before the last four ds_reads into a dead VGPR, s_nop 1 removed; placement kept with 8 bytes of
# baseline (speedup 1.0000x reference)
.LBB0_277:
	s_waitcnt vmcnt(0) lgkmcnt(0)
	s_cbranch_execz .LBB0_265
	s_branch .LBB0_266
	s_nop 0
	s_nop 0
.LBB0_274:
	s_add_i32 s10, s44, 0xfffe8000
	s_and_b32 s10, s10, 0x10000
	v_add_u32_e32 v237, s10, v222
	v_add_u32_e32 v80, v237, v223
	v_add_u32_e32 v236, s10, v233
	s_and_b32 s11, s44, 0x18000
	s_add_i32 s11, s93, s11
	ds_read_b128 v[96:99], v80 offset:32768
	ds_read_b128 v[184:187], v80 offset:40960
	v_add_u32_e32 v80, v237, v225
	ds_read_b128 v[180:183], v80 offset:32768
	ds_read_b128 v[176:179], v80 offset:40960
	v_add_u32_e32 v80, v236, v228
	v_mov_b32_e32 v81, v190
	ds_read_b128 v[172:175], v80 offset:16384
	ds_read_b128 v[168:171], v80 offset:20480
	ds_read_b128 v[164:167], v80 offset:24576
	ds_read_b128 v[160:163], v80 offset:28672
	v_permlane32_swap_b32_e32 v190, v81
	v_cmp_lt_f32_e32 vcc, s13, v190
	s_cbranch_vccz .LBB0_276
	v_max_f32_e32 v64, v190, v190
	v_max_f32_e32 v65, 0, v64
	v_exp_f32_e64 v80, -v65
	v_add_f32_e32 v229, v229, v65
	v_xor_b32_e32 v64, 0x80000000, v229
	v_sub_f32_e32 v127, v127, v65
	v_sub_f32_e32 v126, v126, v65
	v_sub_f32_e32 v125, v125, v65
	v_sub_f32_e32 v124, v124, v65
	v_sub_f32_e32 v123, v123, v65
	v_sub_f32_e32 v122, v122, v65
	v_sub_f32_e32 v121, v121, v65
	v_sub_f32_e32 v120, v120, v65
	v_sub_f32_e32 v119, v119, v65
	v_sub_f32_e32 v118, v118, v65
	v_sub_f32_e32 v117, v117, v65
	v_sub_f32_e32 v116, v116, v65
	v_sub_f32_e32 v115, v115, v65
	v_sub_f32_e32 v114, v114, v65
	v_sub_f32_e32 v113, v113, v65
	v_sub_f32_e32 v112, v112, v65
	v_sub_f32_e32 v143, v143, v65
	v_sub_f32_e32 v142, v142, v65
	v_sub_f32_e32 v141, v141, v65
	v_sub_f32_e32 v140, v140, v65
	v_sub_f32_e32 v139, v139, v65
	v_sub_f32_e32 v138, v138, v65
	v_sub_f32_e32 v137, v137, v65
	v_sub_f32_e32 v136, v136, v65
	v_sub_f32_e32 v135, v135, v65
	v_sub_f32_e32 v134, v134, v65
	v_sub_f32_e32 v133, v133, v65
	v_sub_f32_e32 v132, v132, v65
	v_sub_f32_e32 v131, v131, v65
	v_sub_f32_e32 v130, v130, v65
	v_sub_f32_e32 v129, v129, v65
	v_sub_f32_e32 v128, v128, v65
	v_mov_b32_e32 v65, v64
	v_mov_b32_e32 v66, v64
	v_mov_b32_e32 v67, v64
	v_mov_b32_e32 v68, v64
	v_mov_b32_e32 v69, v64
	v_mov_b32_e32 v70, v64
	v_mov_b32_e32 v71, v64
	v_mov_b32_e32 v72, v64
	v_mov_b32_e32 v73, v64
	v_mov_b32_e32 v74, v64
	v_mov_b32_e32 v75, v64
	v_mov_b32_e32 v76, v64
	v_mov_b32_e32 v77, v64
	v_mov_b32_e32 v78, v64
	v_mov_b32_e32 v79, v64
	v_pk_mul_f32 v[62:63], v[62:63], v[80:81] op_sel_hi:[1,0]
	v_pk_mul_f32 v[60:61], v[60:61], v[80:81] op_sel_hi:[1,0]
	v_pk_mul_f32 v[58:59], v[58:59], v[80:81] op_sel_hi:[1,0]
	v_pk_mul_f32 v[56:57], v[56:57], v[80:81] op_sel_hi:[1,0]
	v_pk_mul_f32 v[54:55], v[54:55], v[80:81] op_sel_hi:[1,0]
	v_pk_mul_f32 v[52:53], v[52:53], v[80:81] op_sel_hi:[1,0]
	v_pk_mul_f32 v[50:51], v[50:51], v[80:81] op_sel_hi:[1,0]
	v_pk_mul_f32 v[48:49], v[48:49], v[80:81] op_sel_hi:[1,0]
	v_pk_mul_f32 v[46:47], v[46:47], v[80:81] op_sel_hi:[1,0]
	v_pk_mul_f32 v[44:45], v[44:45], v[80:81] op_sel_hi:[1,0]
	v_pk_mul_f32 v[42:43], v[42:43], v[80:81] op_sel_hi:[1,0]
	v_pk_mul_f32 v[40:41], v[40:41], v[80:81] op_sel_hi:[1,0]
	v_pk_mul_f32 v[38:39], v[38:39], v[80:81] op_sel_hi:[1,0]
	v_pk_mul_f32 v[36:37], v[36:37], v[80:81] op_sel_hi:[1,0]
	v_pk_mul_f32 v[34:35], v[34:35], v[80:81] op_sel_hi:[1,0]
	v_pk_mul_f32 v[32:33], v[32:33], v[80:81] op_sel_hi:[1,0]
	v_pk_mul_f32 v[14:15], v[14:15], v[80:81] op_sel_hi:[1,0]
	v_pk_mul_f32 v[12:13], v[12:13], v[80:81] op_sel_hi:[1,0]
	v_pk_mul_f32 v[10:11], v[10:11], v[80:81] op_sel_hi:[1,0]
	v_pk_mul_f32 v[8:9], v[8:9], v[80:81] op_sel_hi:[1,0]
	v_pk_mul_f32 v[6:7], v[6:7], v[80:81] op_sel_hi:[1,0]
	v_pk_mul_f32 v[4:5], v[4:5], v[80:81] op_sel_hi:[1,0]
	v_pk_mul_f32 v[2:3], v[2:3], v[80:81] op_sel_hi:[1,0]
	v_pk_mul_f32 v[0:1], v[0:1], v[80:81] op_sel_hi:[1,0]
	v_pk_mul_f32 v[30:31], v[30:31], v[80:81] op_sel_hi:[1,0]
	v_pk_mul_f32 v[28:29], v[28:29], v[80:81] op_sel_hi:[1,0]
	v_pk_mul_f32 v[26:27], v[26:27], v[80:81] op_sel_hi:[1,0]
	v_pk_mul_f32 v[24:25], v[24:25], v[80:81] op_sel_hi:[1,0]
	v_pk_mul_f32 v[22:23], v[22:23], v[80:81] op_sel_hi:[1,0]
	v_pk_mul_f32 v[20:21], v[20:21], v[80:81] op_sel_hi:[1,0]
	v_pk_mul_f32 v[18:19], v[18:19], v[80:81] op_sel_hi:[1,0]
	v_pk_mul_f32 v[16:17], v[16:17], v[80:81] op_sel_hi:[1,0]
	v_pk_mul_f32 v[188:189], v[188:189], v[80:81] op_sel_hi:[1,0]

.LBB0_279:
	s_add_i32 s10, s44, 0xfffe8000
	s_and_b32 s10, s10, 0x10000
	s_xor_b32 s11, s10, 0x10000
	v_add_u32_e32 v209, s11, v224
	v_add_u32_e32 v112, v209, v223
	v_add_u32_e32 v208, s10, v234
	s_add_i32 s10, s93, s10
	ds_read_b128 v[128:131], v112
	ds_read_b128 v[184:187], v112 offset:8192
	v_add_u32_e32 v112, v209, v225
	ds_read_b128 v[180:183], v112
	ds_read_b128 v[176:179], v112 offset:8192
	v_add_u32_e32 v112, v208, v228
	v_mov_b32_e32 v113, v190
	ds_read_b128 v[172:175], v112 offset:49152
	ds_read_b128 v[168:171], v112 offset:53248
	ds_read_b128 v[164:167], v112 offset:57344
	ds_read_b128 v[160:163], v112 offset:61440
	v_permlane32_swap_b32_e32 v190, v113
	v_cmp_lt_f32_e32 vcc, s13, v190
	s_cbranch_vccz .LBB0_281
	v_max_f32_e32 v64, v190, v190
	v_max_f32_e32 v65, 0, v64
	v_exp_f32_e64 v112, -v65
	v_add_f32_e32 v229, v229, v65
	v_xor_b32_e32 v64, 0x80000000, v229
	v_sub_f32_e32 v95, v95, v65
	v_sub_f32_e32 v94, v94, v65
	v_sub_f32_e32 v93, v93, v65
	v_sub_f32_e32 v92, v92, v65
	v_sub_f32_e32 v91, v91, v65
	v_sub_f32_e32 v90, v90, v65
	v_sub_f32_e32 v89, v89, v65
	v_sub_f32_e32 v88, v88, v65
	v_sub_f32_e32 v87, v87, v65
	v_sub_f32_e32 v86, v86, v65
	v_sub_f32_e32 v85, v85, v65
	v_sub_f32_e32 v84, v84, v65
	v_sub_f32_e32 v83, v83, v65
	v_sub_f32_e32 v82, v82, v65
	v_sub_f32_e32 v81, v81, v65
	v_sub_f32_e32 v80, v80, v65
	v_sub_f32_e32 v111, v111, v65
	v_sub_f32_e32 v110, v110, v65
	v_sub_f32_e32 v109, v109, v65
	v_sub_f32_e32 v108, v108, v65
	v_sub_f32_e32 v107, v107, v65
	v_sub_f32_e32 v106, v106, v65
	v_sub_f32_e32 v105, v105, v65
	v_sub_f32_e32 v104, v104, v65
	v_sub_f32_e32 v103, v103, v65
	v_sub_f32_e32 v102, v102, v65
	v_sub_f32_e32 v101, v101, v65
	v_sub_f32_e32 v100, v100, v65
	v_sub_f32_e32 v99, v99, v65
	v_sub_f32_e32 v98, v98, v65
	v_sub_f32_e32 v97, v97, v65
	v_sub_f32_e32 v96, v96, v65
	v_mov_b32_e32 v65, v64
	v_mov_b32_e32 v66, v64
	v_mov_b32_e32 v67, v64
	v_mov_b32_e32 v68, v64
	v_mov_b32_e32 v69, v64
	v_mov_b32_e32 v70, v64
	v_mov_b32_e32 v71, v64
	v_mov_b32_e32 v72, v64
	v_mov_b32_e32 v73, v64
	v_mov_b32_e32 v74, v64
	v_mov_b32_e32 v75, v64
	v_mov_b32_e32 v76, v64
	v_mov_b32_e32 v77, v64
	v_mov_b32_e32 v78, v64
	v_mov_b32_e32 v79, v64
	v_pk_mul_f32 v[62:63], v[62:63], v[112:113] op_sel_hi:[1,0]
	v_pk_mul_f32 v[60:61], v[60:61], v[112:113] op_sel_hi:[1,0]
	v_pk_mul_f32 v[58:59], v[58:59], v[112:113] op_sel_hi:[1,0]
	v_pk_mul_f32 v[56:57], v[56:57], v[112:113] op_sel_hi:[1,0]
	v_pk_mul_f32 v[54:55], v[54:55], v[112:113] op_sel_hi:[1,0]
	v_pk_mul_f32 v[52:53], v[52:53], v[112:113] op_sel_hi:[1,0]
	v_pk_mul_f32 v[50:51], v[50:51], v[112:113] op_sel_hi:[1,0]
	v_pk_mul_f32 v[48:49], v[48:49], v[112:113] op_sel_hi:[1,0]
	v_pk_mul_f32 v[46:47], v[46:47], v[112:113] op_sel_hi:[1,0]
	v_pk_mul_f32 v[44:45], v[44:45], v[112:113] op_sel_hi:[1,0]
	v_pk_mul_f32 v[42:43], v[42:43], v[112:113] op_sel_hi:[1,0]
	v_pk_mul_f32 v[40:41], v[40:41], v[112:113] op_sel_hi:[1,0]
	v_pk_mul_f32 v[38:39], v[38:39], v[112:113] op_sel_hi:[1,0]
	v_pk_mul_f32 v[36:37], v[36:37], v[112:113] op_sel_hi:[1,0]
	v_pk_mul_f32 v[34:35], v[34:35], v[112:113] op_sel_hi:[1,0]
	v_pk_mul_f32 v[32:33], v[32:33], v[112:113] op_sel_hi:[1,0]
	v_pk_mul_f32 v[14:15], v[14:15], v[112:113] op_sel_hi:[1,0]
	v_pk_mul_f32 v[12:13], v[12:13], v[112:113] op_sel_hi:[1,0]
	v_pk_mul_f32 v[10:11], v[10:11], v[112:113] op_sel_hi:[1,0]
	v_pk_mul_f32 v[8:9], v[8:9], v[112:113] op_sel_hi:[1,0]
	v_pk_mul_f32 v[6:7], v[6:7], v[112:113] op_sel_hi:[1,0]
	v_pk_mul_f32 v[4:5], v[4:5], v[112:113] op_sel_hi:[1,0]
	v_pk_mul_f32 v[2:3], v[2:3], v[112:113] op_sel_hi:[1,0]
	v_pk_mul_f32 v[0:1], v[0:1], v[112:113] op_sel_hi:[1,0]
	v_pk_mul_f32 v[30:31], v[30:31], v[112:113] op_sel_hi:[1,0]
	v_pk_mul_f32 v[28:29], v[28:29], v[112:113] op_sel_hi:[1,0]
	v_pk_mul_f32 v[26:27], v[26:27], v[112:113] op_sel_hi:[1,0]
	v_pk_mul_f32 v[24:25], v[24:25], v[112:113] op_sel_hi:[1,0]
	v_pk_mul_f32 v[22:23], v[22:23], v[112:113] op_sel_hi:[1,0]
	v_pk_mul_f32 v[20:21], v[20:21], v[112:113] op_sel_hi:[1,0]
	v_pk_mul_f32 v[18:19], v[18:19], v[112:113] op_sel_hi:[1,0]
	v_pk_mul_f32 v[16:17], v[16:17], v[112:113] op_sel_hi:[1,0]
	v_pk_mul_f32 v[188:189], v[188:189], v[112:113] op_sel_hi:[1,0]
